# P0: idle workgroups pre-touch the w_ada lines that the adaLN workgroups of their XCD stream (L2 warming across workgroups)
# speedup vs baseline: 1.0064x; 1.0064x over previous
.Lwarm0:
	s_cmpk_lg_i32 s82, 0x100
	s_cbranch_scc1 .LBB0_36
	s_and_b32 s1, s0, 7
	s_sub_i32 s6, s0, 48
	s_lshr_b32 s6, s6, 3
	s_lshl_b32 s6, s6, 9
	v_add_u32_e32 v0, s6, v193
	s_waitcnt lgkmcnt(0)
	v_lshrrev_b32_e32 v1, 12, v0
	v_bfe_u32 v2, v0, 2, 10
	v_and_b32_e32 v3, 3, v0
	v_mul_u32_u24_e32 v4, 0x6000, v2
	v_lshl_add_u32 v5, v1, 3, s1
	v_lshl_add_u32 v4, v5, 9, v4
	v_lshl_add_u32 v4, v3, 7, v4
	global_load_dword v6, v4, s[68:69]
	v_add_u32_e32 v0, 0x3400, v0
	s_movk_i32 s6, 0x6000
	v_cmp_gt_u32_e32 vcc, s6, v0
	s_and_saveexec_b64 s[6:7], vcc
	v_lshrrev_b32_e32 v1, 12, v0
	v_bfe_u32 v2, v0, 2, 10
	v_and_b32_e32 v3, 3, v0
	v_mul_u32_u24_e32 v4, 0x6000, v2
	v_lshl_add_u32 v5, v1, 3, s1
	v_lshl_add_u32 v4, v5, 9, v4
	v_lshl_add_u32 v4, v3, 7, v4
	global_load_dword v7, v4, s[68:69]
	s_or_b64 exec, exec, s[6:7]
	s_waitcnt vmcnt(0)
	s_branch .LBB0_36
